# c55 with the dilated-attention item-loop top placed at byte offset 32 mod 64 (cold-path padding only; in-projection, GLA and out-projection loop offsets unchanged)
# baseline (speedup 1.0000x reference)
; DI void tok0_mix_dil(ldsp lds, const Params& p, const float* P, float* BRo, int task, int tid, int wid, int lane) {
;     ...
;             if (lane == 0) S18[pi] = t;
;         }
;         __syncthreads();
.Ls5t_no3:
	s_or_b64 exec, exec, s[22:23]
	s_branch .LBB0_120
	s_nop 1
	s_nop 0
	s_nop 0
	s_nop 0
	s_nop 0
	s_nop 0
	s_nop 0
	s_nop 0
	s_nop 0
	s_nop 0
	s_nop 0
	s_nop 0
	s_nop 0
	s_nop 0
	s_nop 0
	s_nop 0
	s_nop 0
	s_nop 0
	s_nop 0
	s_nop 0

; __global__ void __launch_bounds__(NTHREADS, 2) megak(Params p) {
;     ...
;                 dil_attn_phase(lds, PJ, par ? OBUF2 : OBUF, LSE + par * LSE_SLAB, ROPE, SLAB_B * 288, pv, tid, wid, lane);
;                 if (gridDim.x == 256) {
;                     const int grp = blockIdx.x >> 3;
;                     for (int j = 0; j < 2; ++j) mem_attn_item(lds, PJ, DIL_N, DB_QM, DB_GATE, kvl, BR, st.b0, ((blockIdx.x & 7) * 2 + j) + 16 * grp, tid, wid, lane, j == 0);
;                 } else
;                 for (int it = blockIdx.x; it < SLAB_B * 64; it += gridDim.x) mem_attn_item(lds, PJ, DIL_N, DB_QM, DB_GATE, kvl, BR, st.b0, it, tid, wid, lane);
.LBB0_436:
	s_nop 0
	s_nop 0
	s_nop 0
	s_nop 0
	s_nop 0
	s_nop 0
	s_nop 0
	s_nop 0
	s_nop 0
	s_nop 0
	s_nop 0
	s_nop 0
	s_nop 0
	s_nop 0
	s_nop 0
	v_readlane_b32 s72, v254, 58
	v_readlane_b32 s73, v254, 59
